# residual-GEMM epilogue: touch-prefetch residual rows 2-4 right after row 0 loads (both instances); fixup rewrite; attention LDS pipelining
# speedup vs baseline: 1.0040x; 1.0003x over previous
; #define GAS __attribute__((address_space(1)))
;     __device__ __forceinline__ const float* resrow(int row, int colb) const { return (row < 8192 ? res0 + (size_t)row * DM : res1 + (size_t)(row - 8192) * DM) + colb; }
;     __device__ __forceinline__ void operator()(f32x4 (&acc)[2][2][4][2], const Unit& u, int wr, int wc, int fr, int fq) const {
;     ...
;         { const int lane = fr + 16 * fq, cL = u.pn * BM + wc * 32 + (lane < 32 ? lane : 96 + lane);
;           float vg = 0.f, vb = 0.f, vt = 0.f;
;           if (hasln) { vg = *(const GAS float*)(pg + cL); vb = *(const GAS float*)(pb + cL); }
;           if (haszh) vt = *(const GAS float*)(tg + cL);
;           const float* rp = resrow(row0, colb);
; #pragma unroll
;           for (int bj = 0; bj < 2; ++bj) { rn[bj][0] = ldg4(rp + bj * HALF); rn[bj][1] = ldg4(rp + bj * HALF + 4); }
;           if (hasln) stn = ldg2(pstats + 2 * (size_t)row0);
;           asm volatile("" : "+v"(vg), "+v"(vb), "+v"(vt), "+v"(rn[0][0]), "+v"(rn[0][1]), "+v"(rn[1][0]), "+v"(rn[1][1]), "+v"(stn));
;     ...
;                 if (ai * 4 + m < 7) { const int rown = row0 + ((ai * 4 + m + 1) >> 2) * HALF + ((ai * 4 + m + 1) & 3) * 16; const float* rp = resrow(rown, colb);
; #pragma unroll
;                     for (int bj = 0; bj < 2; ++bj) { rn[bj][0] = ldg4(rp + bj * HALF); rn[bj][1] = ldg4(rp + bj * HALF + 4); }
;                     if (hasln) stn = ldg2(pstats + 2 * (size_t)rown);
;                 }
.LBB0_515:
	v_lshl_add_u32 v188, s82, 8, v1
	v_lshl_add_u64 v[122:123], v[122:123], 2, s[20:21]
	global_load_dword v122, v[122:123], off
	v_add_u32_e32 v123, 0xffffe000, v188
	v_cmp_gt_i32_e32 vcc, s55, v188
	v_ashrrev_i32_e32 v189, 31, v188
	v_mov_b32_e32 v128, s19
	v_cndmask_b32_e32 v126, v123, v188, vcc
	v_mov_b32_e32 v123, s5
	v_cndmask_b32_e32 v127, 0, v189, vcc
	v_cndmask_b32_e32 v129, v123, v128, vcc
	v_mov_b32_e32 v123, s95
	v_mov_b32_e32 v128, s4
	v_or_b32_e32 v190, s15, v204
	v_cndmask_b32_e32 v128, v123, v128, vcc
	v_lshlrev_b64 v[126:127], 13, v[126:127]
	v_lshl_add_u64 v[126:127], v[128:129], 0, v[126:127]
	v_ashrrev_i32_e32 v191, 31, v190
	v_lshl_add_u64 v[126:127], v[190:191], 2, v[126:127]
	global_load_dwordx4 v[154:157], v[126:127], off offset:16
	global_load_dwordx4 v[158:161], v[126:127], off
	global_load_dwordx4 v[146:149], v[126:127], off offset:528
	global_load_dwordx4 v[150:153], v[126:127], off offset:512
	v_add_co_u32_e32 v212, vcc, 0x40000, v126
	s_nop 1
	v_addc_co_u32_e32 v213, vcc, 0, v127, vcc
	global_load_dword v214, v[212:213], off
	global_load_dword v214, v[212:213], off offset:512
	v_add_co_u32_e32 v212, vcc, 0x60000, v126
	s_nop 1
	v_addc_co_u32_e32 v213, vcc, 0, v127, vcc
	global_load_dword v214, v[212:213], off
	global_load_dword v214, v[212:213], off offset:512
	v_add_co_u32_e32 v212, vcc, 0x100000, v126
	s_nop 1
	v_addc_co_u32_e32 v213, vcc, 0, v127, vcc
	global_load_dword v214, v[212:213], off
	global_load_dword v214, v[212:213], off offset:512
	s_and_b64 vcc, exec, s[12:13]
	v_mov_b32_e32 v197, 0
	s_cbranch_vccnz .LBB0_517
	v_lshl_add_u64 v[126:127], v[188:189], 3, s[26:27]
	global_load_dwordx2 v[196:197], v[126:127], off

; #define LAS __attribute__((address_space(3)))
;     __device__ __forceinline__ const float* resrow(int row, int colb) const { return (row < 8192 ? res0 + (size_t)row * DM : res1 + (size_t)(row - 8192) * DM) + colb; }
;     __device__ __forceinline__ void operator()(f32x4 (&acc)[2][2][4][2], const Unit& u, int wr, int wc, int fr, int fq) const {
;     ...
;                 if (ai * 4 + m < 7) { const int rown = row0 + ((ai * 4 + m + 1) >> 2) * HALF + ((ai * 4 + m + 1) & 3) * 16; const float* rp = resrow(rown, colb);
; #pragma unroll
;                     for (int bj = 0; bj < 2; ++bj) { rn[bj][0] = ldg4(rp + bj * HALF); rn[bj][1] = ldg4(rp + bj * HALF + 4); }
;                     if (hasln) stn = ldg2(pstats + 2 * (size_t)rown);
;                 }
;                 float* op = out + (size_t)row * DM + colb; h16* zp = zh + (size_t)row * DM + colb;
;                 float mu = 0.f, rs = 1.f; if (hasln) { mu = st.x * (1.0f / DM); rs = rsqrtf(fmaxf(st.y * (1.0f / DM) - mu * mu, 0.f) + LN_EPS); }
;                 float sm = 0.f, sq = 0.f;
; #pragma unroll
;                 for (int bj = 0; bj < 2; ++bj) {
;                     f32x4 r0 = r[bj][0], r1 = r[bj][1];
;                     if (hasln) { const f32x4 g0 = *(const LAS f32x4*)(slot + bj * 32 + 8 * fq), g1 = *(const LAS f32x4*)(slot + bj * 32 + 8 * fq + 4),
;                                              b0 = *(const LAS f32x4*)(slot + 64 + bj * 32 + 8 * fq), b1 = *(const LAS f32x4*)(slot + 64 + bj * 32 + 8 * fq + 4);
;                         r0 = (r0 - mu) * rs * g0 + b0; r1 = (r1 - mu) * rs * g1 + b1; }
;                     const f32x4 z0 = r0 * ALPHA + acc[ai][bj][m][0], z1 = r1 * ALPHA + acc[ai][bj][m][1];
;                     if (zf == nullptr) { stg4(op + bj * HALF, z0); stg4(op + bj * HALF + 4, z1); }
;                     else { u32x4 w; w.x = pk2(z0[0], z0[1]); w.y = pk2(z0[2], z0[3]); w.z = pk2(z1[0], z1[1]); w.w = pk2(z1[2], z1[3]); stg4h(zf + (size_t)row * DM + colb + bj * HALF, w); }
.LBB0_675:
	v_lshl_add_u32 v184, s89, 8, v1
	v_add_u32_e32 v130, 0xffffe000, v184
	v_ashrrev_i32_e32 v185, 31, v184
	v_cmp_gt_i32_e32 vcc, s55, v184
	v_or_b32_e32 v186, s12, v202
	v_mov_b32_e32 v134, s74
	v_cndmask_b32_e32 v131, 0, v185, vcc
	v_cndmask_b32_e32 v130, v130, v184, vcc
	v_mov_b32_e32 v135, s15
	v_mov_b32_e32 v136, s71
	v_mov_b32_e32 v137, s14
	v_cndmask_b32_e32 v133, v134, v135, vcc
	v_cndmask_b32_e32 v132, v136, v137, vcc
	v_lshlrev_b64 v[130:131], 13, v[130:131]
	v_ashrrev_i32_e32 v187, 31, v186
	v_lshl_add_u64 v[130:131], v[132:133], 0, v[130:131]
	v_lshlrev_b64 v[188:189], 2, v[186:187]
	v_lshl_add_u64 v[130:131], v[130:131], 0, v[188:189]
	v_lshl_add_u64 v[132:133], v[184:185], 3, s[36:37]
	global_load_dwordx4 v[162:165], v[130:131], off offset:16
	global_load_dwordx4 v[170:173], v[130:131], off
	global_load_dwordx2 v[190:191], v[132:133], off
	global_load_dwordx4 v[150:153], v[130:131], off offset:528
	global_load_dwordx4 v[154:157], v[130:131], off offset:512
	v_add_co_u32_e32 v210, vcc, 0x40000, v130
	s_nop 1
	v_addc_co_u32_e32 v211, vcc, 0, v131, vcc
	global_load_dword v212, v[210:211], off
	global_load_dword v212, v[210:211], off offset:512
	v_add_co_u32_e32 v210, vcc, 0x60000, v130
	s_nop 1
	v_addc_co_u32_e32 v211, vcc, 0, v131, vcc
	global_load_dword v212, v[210:211], off
	global_load_dword v212, v[210:211], off offset:512
	v_add_co_u32_e32 v210, vcc, 0x100000, v130
	s_nop 1
	v_addc_co_u32_e32 v211, vcc, 0, v131, vcc
	global_load_dword v212, v[210:211], off
	global_load_dword v212, v[210:211], off offset:512
	v_or_b32_e32 v192, 16, v184
	v_add_u32_e32 v130, 0xffffe010, v184
	v_ashrrev_i32_e32 v193, 31, v192
	v_cmp_gt_i32_e32 vcc, s55, v192
	v_lshl_add_u64 v[194:195], v[192:193], 3, s[36:37]
	v_lshlrev_b64 v[200:201], 11, v[184:185]
	v_cndmask_b32_e32 v131, 0, v193, vcc
	v_cndmask_b32_e32 v130, v130, v192, vcc
	v_cndmask_b32_e32 v133, v134, v135, vcc
	v_cndmask_b32_e32 v132, v136, v137, vcc
	v_lshlrev_b64 v[130:131], 13, v[130:131]
	v_lshl_add_u64 v[130:131], v[132:133], 0, v[130:131]
	v_lshl_add_u64 v[134:135], v[130:131], 0, v[188:189]
	s_mov_b64 s[12:13], -1
	s_waitcnt vmcnt(0)
	global_load_dwordx4 v[138:141], v[134:135], off offset:16
	global_load_dwordx4 v[142:145], v[134:135], off
	global_load_dwordx4 v[130:133], v[134:135], off offset:528
	s_nop 0
	global_load_dwordx4 v[134:137], v[134:135], off offset:512
	s_nop 0
	global_load_dwordx2 v[196:197], v[194:195], off
	v_pk_mul_f32 v[190:191], v[190:191], s[54:55] op_sel_hi:[1,0]
	ds_write2st64_b32 v206, v146, v147 offset1:1
	ds_write_b32 v206, v148 offset:512
	v_fma_f32 v149, -v190, v190, v191
	v_max_f32_e32 v149, 0, v149
	v_add_f32_e32 v149, 0x3727c5ac, v149
	v_mul_f32_e32 v191, 0x4b800000, v149
	v_cmp_gt_f32_e32 vcc, s60, v149
	v_sub_f32_e32 v173, v173, v190
	v_sub_f32_e32 v172, v172, v190
	v_cndmask_b32_e32 v149, v149, v191, vcc
	v_rsq_f32_e32 v149, v149
	v_sub_f32_e32 v171, v171, v190
	v_sub_f32_e32 v170, v170, v190
	v_sub_f32_e32 v165, v165, v190
	v_mul_f32_e32 v146, 0x45800000, v149
	v_cndmask_b32_e32 v194, v149, v146, vcc
	ds_read_b128 v[146:149], v207
	ds_read_b128 v[210:213], v207 offset:16
	ds_read_b128 v[214:217], v207 offset:256
	ds_read_b128 v[222:225], v207 offset:272
	v_sub_f32_e32 v164, v164, v190
	v_sub_f32_e32 v163, v163, v190
	v_sub_f32_e32 v162, v162, v190
	v_pk_mul_f32 v[170:171], v[170:171], v[194:195] op_sel_hi:[1,0]
	v_pk_mul_f32 v[172:173], v[172:173], v[194:195] op_sel_hi:[1,0]
	v_pk_mul_f32 v[162:163], v[162:163], v[194:195] op_sel_hi:[1,0]
	v_pk_mul_f32 v[164:165], v[164:165], v[194:195] op_sel_hi:[1,0]
	s_waitcnt lgkmcnt(0)
	v_pk_fma_f32 v[148:149], v[148:149], v[172:173], v[216:217]
	v_pk_fma_f32 v[146:147], v[146:147], v[170:171], v[214:215]
	v_pk_fma_f32 v[164:165], v[212:213], v[164:165], v[224:225]
	v_pk_fma_f32 v[162:163], v[210:211], v[162:163], v[222:223]
	v_pk_fma_f32 v[126:127], v[146:147], s[94:95], v[126:127] op_sel_hi:[1,0,1]
	v_pk_fma_f32 v[128:129], v[148:149], s[94:95], v[128:129] op_sel_hi:[1,0,1]
	v_pk_fma_f32 v[146:147], v[162:163], s[94:95], v[122:123] op_sel_hi:[1,0,1]
	v_pk_fma_f32 v[148:149], v[164:165], s[94:95], v[124:125] op_sel_hi:[1,0,1]
	s_and_b64 vcc, exec, s[44:45]
	v_lshl_add_u64 v[122:123], v[200:201], 1, s[34:35]
	s_cbranch_vccz .LBB0_677
	v_cvt_pk_f16_f32 v162, v126, v127
	v_cvt_pk_f16_f32 v163, v128, v129
	v_cvt_pk_f16_f32 v164, v146, v147
	v_cvt_pk_f16_f32 v165, v148, v149
	v_lshl_add_u64 v[124:125], v[186:187], 1, v[122:123]
	global_store_dwordx4 v[124:125], v[162:165], off
	s_mov_b64 s[12:13], 0
